# phase-entry pipeline fill: both halves issue K-tile 0 and K-tile 1 staging loads before the first wait (trailing-half stagger barrier deferred to the first K-loop), all 9 GEMM entries
# baseline (speedup 1.0000x reference)
.LBB0_180:
	v_ashrrev_i32_e32 v1, 31, v4
	v_lshrrev_b32_e32 v1, 26, v1
	v_add_u32_e32 v1, v4, v1
	v_ashrrev_i32_e32 v5, 6, v1
	v_bfe_i32 v1, v4, 27, 1
	v_lshlrev_b32_e32 v0, 4, v4
	v_lshrrev_b32_e32 v1, 22, v1
	v_add_u32_e32 v1, v0, v1
	v_and_b32_e32 v1, 0xfffffc00, v1
	s_lshr_b32 s10, s54, 1
	v_sub_u32_e32 v0, v0, v1
	s_lshl_b64 s[28:29], s[10:11], 21
	v_lshrrev_b32_e32 v1, 4, v0
	s_add_u32 s1, s8, s28
	v_bitop3_b32 v0, v1, v0, 32 bitop3:0x6c
	s_addc_u32 s27, s9, s29
	s_lshl_b64 s[28:29], s[10:11], 20
	v_ashrrev_i32_e32 v2, 31, v0
	s_add_u32 s31, s2, s28
	v_lshrrev_b32_e32 v2, 26, v2
	s_addc_u32 s37, s53, s29
	v_add_u32_e32 v2, v0, v2
	s_add_u32 s38, s31, 0x80000
	v_lshlrev_b32_e32 v1, 3, v5
	v_ashrrev_i32_e32 v6, 6, v2
	v_and_b32_e32 v2, 0xc0, v2
	s_addc_u32 s39, s37, 0
	v_and_b32_e32 v1, -16, v1
	v_sub_u32_e32 v0, v0, v2
	s_and_b64 s[28:29], s[4:5], exec
	v_add_u32_e32 v1, v6, v1
	v_ashrrev_i16_sdwa v0, v144, sext(v0) dst_sel:DWORD dst_unused:UNUSED_PAD src0_sel:DWORD src1_sel:BYTE_0
	s_cselect_b32 s64, s27, s39
	s_cselect_b32 s66, s37, s27
	v_lshlrev_b32_e32 v3, 5, v5
	v_bfe_i32 v7, v0, 0, 16
	v_lshlrev_b32_e32 v0, 1, v1
	v_lshrrev_b32_e32 v2, 2, v1
	v_and_b32_e32 v8, 3, v6
	s_mov_b32 s27, 0x1fffe0
	v_and_b32_e32 v3, 32, v3
	v_and_b32_e32 v0, 24, v0
	v_and_b32_e32 v2, 4, v2
	v_and_or_b32 v8, v1, s27, v8
	s_cselect_b32 s68, 8, 32
	v_or3_b32 v0, v8, v2, v0
	v_add_lshl_u32 v2, v3, v7, 1
	v_lshl_add_u32 v130, v1, 11, v2
	v_cvt_f32_ubyte0_e32 v1, s68
	v_rcp_iflag_f32_e32 v1, v1
	v_lshl_add_u32 v128, v0, 11, v2
	s_cselect_b32 s65, s1, s38
	s_cselect_b32 s67, s31, s1
	v_mul_f32_e32 v0, 0x4f7ffffe, v1
	v_cvt_u32_f32_e32 v0, v0
	s_sub_i32 s28, 0, s68
	s_add_i32 s0, s26, s0
	s_abs_i32 s27, s0
	v_readfirstlane_b32 s70, v0
	s_mul_i32 s28, s28, s70
	s_mul_hi_u32 s28, s70, s28
	s_add_i32 s70, s70, s28
	s_mul_hi_u32 s28, s27, s70
	s_mul_i32 s29, s28, s68
	s_ashr_i32 s1, s30, 6
	s_sub_i32 s27, s27, s29
	s_ashr_i32 s37, s30, 8
	s_lshl_b32 s69, s1, 10
	s_ashr_i32 s26, s0, 31
	s_add_i32 s29, s28, 1
	s_sub_i32 s31, s27, s68
	s_cmp_ge_u32 s27, s68
	s_cselect_b32 s28, s29, s28
	s_cselect_b32 s27, s31, s27
	s_add_i32 s29, s28, 1
	s_cmp_ge_u32 s27, s68
	s_cselect_b32 s27, s29, s28
	s_xor_b32 s27, s27, s26
	s_sub_i32 s26, s27, s26
	s_lshl_b32 s28, s26, 3
	s_sub_i32 s27, s55, s28
	s_min_i32 s29, s27, 8
	s_sext_i32_i8 s27, s29
	v_cvt_f32_i32_e32 v0, s27
	s_mul_i32 s26, s26, s68
	s_sub_i32 s31, s0, s26
	v_cvt_f32_i32_e32 v1, s31
	v_rcp_iflag_f32_e32 v2, v0
	s_xor_b32 s0, s31, s27
	s_ashr_i32 s0, s0, 30
	s_or_b32 s0, s0, 1
	v_mul_f32_e32 v2, v1, v2
	v_trunc_f32_e32 v2, v2
	v_fma_f32 v1, -v2, v0, v1
	v_cvt_i32_f32_e32 v2, v2
	v_cmp_ge_f32_e64 s[26:27], |v1|, |v0|
	s_and_b64 s[26:27], s[26:27], exec
	s_cselect_b32 s0, s0, 0
	v_readfirstlane_b32 s26, v2
	s_add_i32 s0, s26, s0
	s_mul_i32 s26, s0, s29
	s_sub_i32 s26, s31, s26
	s_sext_i32_i8 s26, s26
	s_add_i32 s44, s28, s26
	s_ashr_i32 s45, s44, 31
	s_lshl_b64 s[26:27], s[44:45], 19
	s_add_u32 s46, s65, s26
	s_addc_u32 s47, s64, s27
	s_bfe_i64 s[26:27], s[0:1], 0x80000
	s_lshl_b64 s[26:27], s[26:27], 19
	s_add_u32 s48, s67, s26
	s_addc_u32 s49, s66, s27
	s_add_i32 s45, s69, 0
	v_lshl_add_u64 v[0:1], s[48:49], 0, v[128:129]
	s_add_i32 m0, s45, 0x10000
	v_lshl_add_u64 v[2:3], v[0:1], 0, s[12:13]
	global_load_lds_dwordx4 v128, s[48:49]
	s_add_i32 m0, s45, 0x12000
	v_mov_b32_e32 v131, v129
	global_load_lds_dwordx4 v[2:3], off
	v_lshl_add_u64 v[2:3], v[0:1], 0, s[14:15]
	s_add_i32 m0, s45, 0x14000
	s_add_i32 s71, s45, 0x2000
	global_load_lds_dwordx4 v[2:3], off
	v_lshl_add_u64 v[2:3], v[0:1], 0, s[16:17]
	s_add_i32 m0, s45, 0x16000
	s_add_i32 s72, s45, 0x4000
	global_load_lds_dwordx4 v[2:3], off
	v_lshl_add_u64 v[2:3], s[46:47], 0, v[130:131]
	s_mov_b32 m0, s45
	v_lshl_add_u64 v[8:9], v[2:3], 0, s[12:13]
	global_load_lds_dwordx4 v130, s[46:47]
	s_mov_b32 m0, s71
	s_add_i32 s73, s45, 0x6000
	global_load_lds_dwordx4 v[8:9], off
	v_lshl_add_u64 v[8:9], v[2:3], 0, s[14:15]
	s_mov_b32 m0, s72
	s_cmp_eq_u32 s37, 1
	global_load_lds_dwordx4 v[8:9], off
	v_lshl_add_u64 v[8:9], v[2:3], 0, s[16:17]
	s_mov_b32 m0, s73
	s_mov_b32 s88, s76
	global_load_lds_dwordx4 v[8:9], off
	s_cselect_b64 s[26:27], -1, 0
	s_cmp_lg_u32 s37, 1
	s_cbranch_scc1 .LBB0_182
	s_mov_b32 s98, 1

.LBB0_216:
	v_writelane_b32 v254, s26, 60
	v_writelane_b32 v254, s24, 61
	s_xor_b64 s[0:1], s[8:9], -1
	s_and_b64 vcc, exec, s[14:15]
	v_writelane_b32 v254, s25, 62
	s_cbranch_vccz .LBB0_266
	s_cmp_gt_i32 s26, 1
	s_mov_b64 s[14:15], -1
	s_cbranch_scc0 .LBB0_264
	s_cmp_eq_u32 s26, 2
	s_mov_b64 s[12:13], -1
	s_cbranch_scc0 .LBB0_263
	v_readlane_b32 s16, v252, 39
	s_and_b64 s[12:13], s[8:9], exec
	s_movk_i32 s6, 0xa00
	v_readlane_b32 s17, v252, 40
	v_readlane_b32 s18, v252, 41
	v_readlane_b32 s19, v252, 42
	v_readlane_b32 s20, v252, 43
	v_readlane_b32 s21, v252, 44
	s_cselect_b32 s12, s6, 0x400
	s_mov_b32 s6, 0x5000000
	v_readlane_b32 s22, v252, 45
	v_readlane_b32 s23, v252, 46
	s_mov_b64 s[16:17], s[20:21]
	s_cselect_b32 s6, s6, 0x5500000
	s_mov_b64 s[18:19], s[22:23]
	s_add_u32 s6, s18, s6
	s_addc_u32 s19, s19, 0
	s_lshr_b32 s20, s12, 5
	s_lshr_b32 s70, s12, 1
	s_mov_b64 s[12:13], -1
	s_and_b64 vcc, exec, s[0:1]
	s_cbranch_vccz .LBB0_239
	v_mov_b32_e32 v4, v241
	s_cmp_ge_i32 s87, s70
	v_readfirstlane_b32 s22, v4
	s_cbranch_scc1 .LBB0_238
	v_bfe_i32 v1, v4, 27, 1
	v_lshlrev_b32_e32 v0, 4, v4
	v_lshrrev_b32_e32 v1, 22, v1
	v_add_u32_e32 v1, v0, v1
	v_and_b32_e32 v1, 0xfffffc00, v1
	v_sub_u32_e32 v0, v0, v1
	v_lshrrev_b32_e32 v1, 4, v0
	v_ashrrev_i32_e32 v2, 31, v4
	v_bitop3_b32 v0, v1, v0, 32 bitop3:0x6c
	v_lshrrev_b32_e32 v2, 26, v2
	v_ashrrev_i32_e32 v1, 31, v0
	v_add_u32_e32 v2, v4, v2
	v_lshrrev_b32_e32 v1, 26, v1
	v_ashrrev_i32_e32 v6, 6, v2
	v_add_u32_e32 v1, v0, v1
	v_lshlrev_b32_e32 v2, 3, v6
	v_ashrrev_i32_e32 v5, 6, v1
	v_and_b32_e32 v2, -16, v2
	v_add_u32_e32 v2, v5, v2
	v_and_b32_e32 v3, 3, v5
	s_mov_b32 s12, 0x1fffe0
	v_lshrrev_b32_e32 v7, 2, v2
	v_lshlrev_b32_e32 v8, 1, v2
	v_and_or_b32 v3, v2, s12, v3
	v_and_b32_e32 v7, 4, v7
	v_and_b32_e32 v8, 24, v8
	v_or3_b32 v3, v3, v7, v8
	v_cvt_f32_u32_e32 v8, s20
	v_and_b32_e32 v1, 0xc0, v1
	v_sub_u32_e32 v0, v0, v1
	s_sub_i32 s12, 0, s20
	v_rcp_iflag_f32_e32 v1, v8
	v_readlane_b32 s14, v254, 44
	s_ashr_i32 s29, s22, 6
	s_ashr_i32 s31, s22, 8
	v_mul_f32_e32 v1, 0x4f7ffffe, v1
	v_cvt_u32_f32_e32 v1, v1
	s_lshl_b32 s23, s29, 10
	v_lshlrev_b32_e32 v7, 5, v6
	v_ashrrev_i16_sdwa v0, v238, sext(v0) dst_sel:DWORD dst_unused:UNUSED_PAD src0_sel:DWORD src1_sel:BYTE_0
	v_readfirstlane_b32 s24, v1
	s_mul_i32 s12, s12, s24
	s_mul_hi_u32 s12, s24, s12
	s_add_i32 s24, s24, s12
	s_mul_hi_u32 s12, s14, s24
	s_mul_i32 s13, s12, s20
	s_sub_i32 s13, s14, s13
	s_add_i32 s14, s12, 1
	s_sub_i32 s15, s13, s20
	s_cmp_ge_u32 s13, s20
	s_cselect_b32 s12, s14, s12
	s_cselect_b32 s13, s15, s13
	s_add_i32 s14, s12, 1
	s_cmp_ge_u32 s13, s20
	s_cselect_b32 s12, s14, s12
	v_readlane_b32 s13, v254, 42
	s_xor_b32 s12, s12, s13
	s_sub_i32 s12, s12, s13
	s_lshl_b32 s14, s12, 3
	s_sub_i32 s13, 0x80, s14
	v_and_b32_e32 v9, 32, v7
	v_bfe_i32 v7, v0, 0, 16
	s_min_i32 s15, s13, 8
	v_add_lshl_u32 v0, v9, v7, 1
	s_sext_i32_i16 s13, s15
	v_lshl_add_u32 v128, v3, 11, v0
	v_lshl_add_u32 v130, v2, 11, v0
	v_cvt_f32_i32_e32 v0, s13
	s_mul_i32 s12, s12, s20
	v_readlane_b32 s16, v254, 43
	s_sub_i32 s16, s16, s12
	s_sext_i32_i16 s12, s16
	v_cvt_f32_i32_e32 v1, s12
	v_rcp_iflag_f32_e32 v2, v0
	s_xor_b32 s12, s12, s13
	s_ashr_i32 s12, s12, 30
	s_or_b32 s17, s12, 1
	v_mul_f32_e32 v2, v1, v2
	v_trunc_f32_e32 v2, v2
	v_fma_f32 v1, -v2, v0, v1
	v_cvt_i32_f32_e32 v2, v2
	v_cmp_ge_f32_e64 s[12:13], |v1|, |v0|
	s_and_b64 s[12:13], s[12:13], exec
	s_cselect_b32 s12, s17, 0
	v_readfirstlane_b32 s13, v2
	s_add_i32 s36, s13, s12
	s_mul_i32 s12, s36, s15
	s_sub_i32 s12, s16, s12
	s_sext_i32_i16 s12, s12
	s_add_i32 s50, s14, s12
	s_ashr_i32 s51, s50, 31
	s_lshl_b64 s[12:13], s[50:51], 19
	s_add_u32 s14, s64, s12
	s_addc_u32 s15, s65, s13
	s_bfe_i64 s[12:13], s[36:37], 0x100000
	s_lshl_b64 s[12:13], s[12:13], 19
	s_add_u32 s16, s6, s12
	s_addc_u32 s17, s19, s13
	s_lshl_b32 s12, s50, 8
	s_ashr_i32 s13, s12, 31
	s_lshl_b64 s[12:13], s[12:13], 2
	v_readlane_b32 s26, v252, 63
	v_readlane_b32 s27, v253, 0
	s_add_u32 s12, s26, s12
	s_addc_u32 s13, s27, s13
	v_lshlrev_b32_sdwa v184, v239, v4 dst_sel:DWORD dst_unused:UNUSED_PAD src0_sel:DWORD src1_sel:BYTE_0
	v_lshl_add_u64 v[0:1], s[12:13], 0, v[184:185]
	v_mov_b32_e32 v129, v185
	s_add_i32 s25, s23, 0
	global_load_dword v136, v[0:1], off
	v_lshl_add_u64 v[0:1], s[16:17], 0, v[128:129]
	s_add_i32 m0, s25, 0x10000
	v_lshl_add_u64 v[2:3], v[0:1], 0, s[34:35]
	global_load_lds_dwordx4 v128, s[16:17]
	s_add_i32 m0, s25, 0x12000
	v_mov_b32_e32 v131, v185
	global_load_lds_dwordx4 v[2:3], off
	v_lshl_add_u64 v[2:3], v[0:1], 0, s[92:93]
	s_add_i32 m0, s25, 0x14000
	s_add_i32 s26, s25, 0x2000
	global_load_lds_dwordx4 v[2:3], off
	v_lshl_add_u64 v[2:3], v[0:1], 0, s[52:53]
	s_add_i32 m0, s25, 0x16000
	s_add_i32 s27, s25, 0x4000
	global_load_lds_dwordx4 v[2:3], off
	v_lshl_add_u64 v[2:3], s[14:15], 0, v[130:131]
	s_mov_b32 m0, s25
	v_lshl_add_u64 v[8:9], v[2:3], 0, s[34:35]
	global_load_lds_dwordx4 v130, s[14:15]
	s_mov_b32 m0, s26
	s_add_i32 s28, s25, 0x6000
	global_load_lds_dwordx4 v[8:9], off
	v_lshl_add_u64 v[8:9], v[2:3], 0, s[92:93]
	s_mov_b32 m0, s27
	s_cmp_eq_u32 s31, 1
	global_load_lds_dwordx4 v[8:9], off
	v_lshl_add_u64 v[8:9], v[2:3], 0, s[52:53]
	s_mov_b32 m0, s28
	s_cselect_b64 s[12:13], -1, 0
	global_load_lds_dwordx4 v[8:9], off
	s_cmp_lg_u32 s31, 1
	s_cbranch_scc1 .LBB0_223
	s_mov_b32 s98, 1

.LBB0_239:
	s_andn2_b64 vcc, exec, s[12:13]
	s_cbranch_vccnz .LBB0_262
	v_mov_b32_e32 v4, v241
	s_cmp_ge_i32 s87, s70
	v_readfirstlane_b32 s31, v4
	s_cbranch_scc1 .LBB0_262
	v_bfe_i32 v1, v4, 27, 1
	v_lshlrev_b32_e32 v0, 4, v4
	v_lshrrev_b32_e32 v1, 22, v1
	v_add_u32_e32 v1, v0, v1
	v_and_b32_e32 v1, 0xfffffc00, v1
	v_sub_u32_e32 v0, v0, v1
	v_lshrrev_b32_e32 v1, 4, v0
	v_ashrrev_i32_e32 v2, 31, v4
	v_bitop3_b32 v0, v1, v0, 32 bitop3:0x6c
	v_lshrrev_b32_e32 v2, 26, v2
	v_ashrrev_i32_e32 v1, 31, v0
	v_add_u32_e32 v2, v4, v2
	v_lshrrev_b32_e32 v1, 26, v1
	v_ashrrev_i32_e32 v6, 6, v2
	v_add_u32_e32 v1, v0, v1
	v_lshlrev_b32_e32 v2, 3, v6
	v_ashrrev_i32_e32 v5, 6, v1
	v_and_b32_e32 v2, -16, v2
	v_add_u32_e32 v2, v5, v2
	v_and_b32_e32 v3, 3, v5
	s_mov_b32 s12, 0x1fffe0
	v_lshrrev_b32_e32 v7, 2, v2
	v_lshlrev_b32_e32 v8, 1, v2
	v_and_or_b32 v3, v2, s12, v3
	v_and_b32_e32 v7, 4, v7
	v_and_b32_e32 v8, 24, v8
	v_or3_b32 v3, v3, v7, v8
	v_cvt_f32_u32_e32 v8, s20
	v_and_b32_e32 v1, 0xc0, v1
	v_sub_u32_e32 v0, v0, v1
	s_sub_i32 s12, 0, s20
	v_rcp_iflag_f32_e32 v1, v8
	v_readlane_b32 s14, v254, 47
	s_ashr_i32 s29, s31, 6
	s_ashr_i32 s22, s31, 8
	v_mul_f32_e32 v1, 0x4f7ffffe, v1
	v_cvt_u32_f32_e32 v1, v1
	s_lshl_b32 s23, s29, 10
	v_lshlrev_b32_e32 v7, 5, v6
	v_ashrrev_i16_sdwa v0, v238, sext(v0) dst_sel:DWORD dst_unused:UNUSED_PAD src0_sel:DWORD src1_sel:BYTE_0
	v_readfirstlane_b32 s24, v1
	s_mul_i32 s12, s12, s24
	s_mul_hi_u32 s12, s24, s12
	s_add_i32 s24, s24, s12
	s_mul_hi_u32 s12, s14, s24
	s_mul_i32 s13, s12, s20
	s_sub_i32 s13, s14, s13
	s_add_i32 s14, s12, 1
	s_sub_i32 s15, s13, s20
	s_cmp_ge_u32 s13, s20
	s_cselect_b32 s12, s14, s12
	s_cselect_b32 s13, s15, s13
	s_add_i32 s14, s12, 1
	s_cmp_ge_u32 s13, s20
	s_cselect_b32 s12, s14, s12
	v_readlane_b32 s13, v254, 45
	s_xor_b32 s12, s12, s13
	s_sub_i32 s12, s12, s13
	s_lshl_b32 s14, s12, 3
	s_sub_i32 s13, 0x80, s14
	v_and_b32_e32 v9, 32, v7
	v_bfe_i32 v7, v0, 0, 16
	s_min_i32 s15, s13, 8
	v_add_lshl_u32 v0, v9, v7, 1
	s_sext_i32_i16 s13, s15
	v_lshl_add_u32 v128, v3, 11, v0
	v_lshl_add_u32 v130, v2, 11, v0
	v_cvt_f32_i32_e32 v0, s13
	s_mul_i32 s12, s12, s20
	v_readlane_b32 s16, v254, 46
	s_sub_i32 s16, s16, s12
	s_sext_i32_i16 s12, s16
	v_cvt_f32_i32_e32 v1, s12
	v_rcp_iflag_f32_e32 v2, v0
	s_xor_b32 s12, s12, s13
	s_ashr_i32 s12, s12, 30
	s_or_b32 s17, s12, 1
	v_mul_f32_e32 v2, v1, v2
	v_trunc_f32_e32 v2, v2
	v_fma_f32 v1, -v2, v0, v1
	v_cvt_i32_f32_e32 v2, v2
	v_cmp_ge_f32_e64 s[12:13], |v1|, |v0|
	s_and_b64 s[12:13], s[12:13], exec
	s_cselect_b32 s12, s17, 0
	v_readfirstlane_b32 s13, v2
	s_add_i32 s36, s13, s12
	s_mul_i32 s12, s36, s15
	s_sub_i32 s12, s16, s12
	s_sext_i32_i16 s12, s12
	s_add_i32 s50, s14, s12
	s_ashr_i32 s51, s50, 31
	s_lshl_b64 s[12:13], s[50:51], 19
	s_add_u32 s14, s64, s12
	s_addc_u32 s15, s65, s13
	s_bfe_i64 s[12:13], s[36:37], 0x100000
	s_lshl_b64 s[12:13], s[12:13], 19
	s_add_u32 s16, s6, s12
	s_addc_u32 s17, s19, s13
	s_lshl_b32 s12, s50, 8
	s_ashr_i32 s13, s12, 31
	s_lshl_b64 s[12:13], s[12:13], 2
	v_readlane_b32 s26, v252, 49
	v_readlane_b32 s27, v252, 50
	s_add_u32 s12, s26, s12
	s_addc_u32 s13, s27, s13
	v_lshlrev_b32_sdwa v184, v239, v4 dst_sel:DWORD dst_unused:UNUSED_PAD src0_sel:DWORD src1_sel:BYTE_0
	v_lshl_add_u64 v[0:1], s[12:13], 0, v[184:185]
	v_mov_b32_e32 v129, v185
	s_add_i32 s25, s23, 0
	global_load_dword v136, v[0:1], off
	v_lshl_add_u64 v[0:1], s[16:17], 0, v[128:129]
	s_add_i32 m0, s25, 0x10000
	v_lshl_add_u64 v[2:3], v[0:1], 0, s[34:35]
	global_load_lds_dwordx4 v128, s[16:17]
	s_add_i32 m0, s25, 0x12000
	v_mov_b32_e32 v131, v185
	global_load_lds_dwordx4 v[2:3], off
	v_lshl_add_u64 v[2:3], v[0:1], 0, s[92:93]
	s_add_i32 m0, s25, 0x14000
	s_add_i32 s26, s25, 0x2000
	global_load_lds_dwordx4 v[2:3], off
	v_lshl_add_u64 v[2:3], v[0:1], 0, s[52:53]
	s_add_i32 m0, s25, 0x16000
	s_add_i32 s27, s25, 0x4000
	global_load_lds_dwordx4 v[2:3], off
	v_lshl_add_u64 v[2:3], s[14:15], 0, v[130:131]
	s_mov_b32 m0, s25
	v_lshl_add_u64 v[8:9], v[2:3], 0, s[34:35]
	global_load_lds_dwordx4 v130, s[14:15]
	s_mov_b32 m0, s26
	s_add_i32 s28, s25, 0x6000
	global_load_lds_dwordx4 v[8:9], off
	v_lshl_add_u64 v[8:9], v[2:3], 0, s[92:93]
	s_mov_b32 m0, s27
	s_cmp_eq_u32 s22, 1
	global_load_lds_dwordx4 v[8:9], off
	v_lshl_add_u64 v[8:9], v[2:3], 0, s[52:53]
	s_mov_b32 m0, s28
	s_cselect_b64 s[12:13], -1, 0
	global_load_lds_dwordx4 v[8:9], off
	s_cmp_lg_u32 s22, 1
	s_cbranch_scc1 .LBB0_243
	s_mov_b32 s98, 1

.LBB0_298:
	s_and_b64 s[12:13], s[8:9], exec
	s_cselect_b32 s60, s67, s73
	s_cselect_b32 s61, s66, s72
	s_mov_b64 s[14:15], -1
	s_mov_b64 s[12:13], 0
	s_andn2_b64 vcc, exec, s[0:1]
	s_mov_b64 s[0:1], 0
	s_cbranch_vccnz .LBB0_342
	v_readlane_b32 s14, v254, 58
	v_readlane_b32 s15, v254, 59
	s_mov_b64 s[0:1], -1
	s_and_b64 vcc, exec, s[14:15]
	s_cbranch_vccz .LBB0_341
	v_readlane_b32 s0, v253, 3
	v_mov_b32_e32 v8, v241
	v_readlane_b32 s1, v253, 4
	s_andn2_b64 vcc, exec, s[0:1]
	v_readfirstlane_b32 s0, v8
	s_cbranch_vccnz .LBB0_340
	v_bfe_i32 v1, v8, 27, 1
	v_lshlrev_b32_e32 v0, 4, v8
	v_lshrrev_b32_e32 v1, 22, v1
	v_add_u32_e32 v1, v0, v1
	v_and_b32_e32 v1, 0xfffffc00, v1
	v_sub_u32_e32 v0, v0, v1
	v_lshrrev_b32_e32 v1, 4, v0
	v_ashrrev_i32_e32 v2, 31, v8
	v_bitop3_b32 v0, v1, v0, 32 bitop3:0x6c
	v_lshrrev_b32_e32 v2, 26, v2
	v_ashrrev_i32_e32 v1, 31, v0
	v_add_u32_e32 v2, v8, v2
	v_lshrrev_b32_e32 v1, 26, v1
	v_ashrrev_i32_e32 v5, 6, v2
	v_add_u32_e32 v1, v0, v1
	v_lshlrev_b32_e32 v2, 3, v5
	v_ashrrev_i32_e32 v4, 6, v1
	v_and_b32_e32 v2, -16, v2
	v_add_u32_e32 v2, v4, v2
	v_and_b32_e32 v3, 3, v4
	s_mov_b32 s14, 0x1ffffe0
	v_lshrrev_b32_e32 v6, 2, v2
	v_lshlrev_b32_e32 v7, 1, v2
	v_and_b32_e32 v1, 0xc0, v1
	v_writelane_b32 v254, s23, 63
	v_and_or_b32 v3, v2, s14, v3
	v_and_b32_e32 v6, 4, v6
	v_and_b32_e32 v7, 24, v7
	v_sub_u32_e32 v0, v0, v1
	s_ashr_i32 s1, s0, 6
	v_or3_b32 v3, v3, v6, v7
	s_movk_i32 s14, 0x580
	v_lshlrev_b32_e32 v6, 5, v5
	v_ashrrev_i16_sdwa v0, v238, sext(v0) dst_sel:DWORD dst_unused:UNUSED_PAD src0_sel:DWORD src1_sel:BYTE_0
	v_readlane_b32 s15, v254, 34
	s_ashr_i32 s16, s0, 8
	s_lshl_b32 s6, s1, 10
	v_mul_lo_u32 v3, v3, s14
	v_and_b32_e32 v6, 32, v6
	v_bfe_i32 v7, v0, 0, 16
	v_mul_lo_u32 v1, v2, s14
	s_mul_i32 s14, s15, 0xb0000
	v_add_u32_e32 v0, v6, v7
	s_add_u32 s14, s40, s14
	s_mul_hi_i32 s15, s15, 0xb0000
	v_add_lshl_u32 v184, v3, v0, 1
	s_addc_u32 s15, s41, s15
	s_add_i32 s19, s6, 0
	v_add_lshl_u32 v194, v0, v1, 1
	v_lshl_add_u64 v[0:1], s[14:15], 0, v[184:185]
	s_add_i32 m0, s19, 0x10000
	v_lshl_add_u64 v[2:3], v[0:1], 0, s[42:43]
	global_load_lds_dwordx4 v184, s[14:15]
	s_add_i32 m0, s19, 0x12000
	v_readlane_b32 s20, v254, 38
	global_load_lds_dwordx4 v[2:3], off
	v_lshl_add_u64 v[2:3], v[0:1], 0, s[2:3]
	s_add_i32 m0, s19, 0x14000
	v_mov_b32_e32 v195, v185
	global_load_lds_dwordx4 v[2:3], off
	v_lshl_add_u64 v[2:3], v[0:1], 0, s[48:49]
	s_add_i32 m0, s19, 0x16000
	v_readlane_b32 s21, v254, 39
	global_load_lds_dwordx4 v[2:3], off
	s_mov_b32 m0, s19
	v_lshl_add_u64 v[2:3], s[20:21], 0, v[194:195]
	v_readlane_b32 s22, v254, 40
	s_nop 0
	global_load_lds_dwordx4 v194, s[20:21]
	s_add_i32 s20, s19, 0x2000
	v_lshl_add_u64 v[10:11], v[2:3], 0, s[42:43]
	s_mov_b32 m0, s20
	v_readlane_b32 s23, v254, 41
	s_add_i32 s25, s19, 0x4000
	global_load_lds_dwordx4 v[10:11], off
	v_lshl_add_u64 v[10:11], s[22:23], 0, v[194:195]
	s_mov_b32 m0, s25
	s_add_i32 s26, s19, 0x6000
	global_load_lds_dwordx4 v194, s[22:23]
	v_lshl_add_u64 v[10:11], v[10:11], 0, s[42:43]
	s_mov_b32 m0, s26
	v_writelane_b32 v255, s61, 0
	global_load_lds_dwordx4 v[10:11], off
	v_writelane_b32 v255, s60, 1
	v_writelane_b32 v255, s62, 2
	s_cmp_eq_u32 s16, 1
	s_movk_i32 s18, 0x580
	v_writelane_b32 v255, s63, 3
	s_cselect_b64 s[42:43], -1, 0
	s_cmp_lg_u32 s16, 1
	s_cbranch_scc1 .LBB0_303
	s_mov_b32 s98, 1

.LBB0_344:
	s_andn2_b64 vcc, exec, s[0:1]
	v_readlane_b32 s0, v253, 3
	v_readlane_b32 s1, v253, 4
	s_nop 1
	v_cndmask_b32_e64 v0, 0, 1, s[0:1]
	v_cmp_ne_u32_e64 s[14:15], 1, v0
	s_cbranch_vccnz .LBB0_404
	v_mov_b32_e32 v15, v241
	s_and_b64 vcc, exec, s[14:15]
	v_readfirstlane_b32 s0, v15
	s_cbranch_vccnz .LBB0_403
	s_waitcnt lgkmcnt(0)
	v_bfe_i32 v1, v15, 27, 1
	v_lshlrev_b32_e32 v0, 4, v15
	v_lshrrev_b32_e32 v1, 22, v1
	v_add_u32_e32 v1, v0, v1
	v_and_b32_e32 v1, 0xfffffc00, v1
	v_sub_u32_e32 v0, v0, v1
	v_lshrrev_b32_e32 v1, 4, v0
	v_ashrrev_i32_e32 v3, 31, v15
	v_bitop3_b32 v0, v1, v0, 32 bitop3:0x6c
	v_lshrrev_b32_e32 v3, 26, v3
	v_ashrrev_i32_e32 v1, 31, v0
	v_add_u32_e32 v3, v15, v3
	v_lshrrev_b32_e32 v1, 26, v1
	v_ashrrev_i32_e32 v3, 6, v3
	v_add_u32_e32 v1, v0, v1
	v_lshlrev_b32_e32 v4, 3, v3
	v_ashrrev_i32_e32 v2, 6, v1
	v_and_b32_e32 v4, -16, v4
	v_add_u32_e32 v4, v2, v4
	v_and_b32_e32 v2, 3, v2
	s_mov_b32 s12, 0x7fffffe0
	v_writelane_b32 v254, s23, 63
	s_lshl_b32 s26, s23, 9
	v_and_or_b32 v2, v4, s12, v2
	v_readlane_b32 s12, v254, 37
	v_writelane_b32 v255, s14, 2
	v_and_b32_e32 v1, 0xc0, v1
	s_mul_hi_i32 s17, s26, s12
	s_mul_i32 s16, s26, s12
	v_readlane_b32 s12, v254, 35
	v_writelane_b32 v255, s15, 3
	s_ashr_i32 s1, s0, 6
	v_lshrrev_b32_e32 v5, 2, v4
	v_lshlrev_b32_e32 v6, 1, v4
	v_sub_u32_e32 v0, v0, v1
	v_readlane_b32 s13, v254, 36
	s_mov_b32 s14, s12
	s_ashr_i32 s6, s0, 8
	s_lshl_b32 s70, s23, 7
	s_lshl_b32 s44, s23, 8
	s_lshl_b32 s27, s1, 10
	v_and_b32_e32 v5, 4, v5
	v_and_b32_e32 v6, 24, v6
	v_lshlrev_b32_e32 v3, 5, v3
	v_ashrrev_i16_sdwa v0, v238, sext(v0) dst_sel:DWORD dst_unused:UNUSED_PAD src0_sel:DWORD src1_sel:BYTE_0
	s_mul_i32 s13, s26, s14
	v_or3_b32 v2, v2, v5, v6
	v_and_b32_e32 v12, 32, v3
	v_bfe_i32 v13, v0, 0, 16
	s_mul_hi_i32 s12, s26, s12
	s_add_u32 s14, s40, s13
	v_mul_lo_u32 v2, v2, s23
	v_add_u32_e32 v0, v12, v13
	s_addc_u32 s15, s41, s12
	s_add_i32 s28, s27, 0
	v_add_lshl_u32 v184, v2, v0, 1
	s_add_i32 m0, s28, 0x10000
	v_mul_lo_u32 v14, v4, s23
	v_lshl_add_u64 v[4:5], s[14:15], 0, v[184:185]
	global_load_lds_dwordx4 v184, s[14:15]
	s_add_i32 m0, s28, 0x12000
	v_lshl_add_u64 v[6:7], v[4:5], 0, s[70:71]
	s_add_u32 s12, s14, s44
	global_load_lds_dwordx4 v[6:7], off
	s_addc_u32 s13, s15, 0
	s_add_i32 m0, s28, 0x14000
	v_add_lshl_u32 v194, v0, v14, 1
	global_load_lds_dwordx4 v184, s[12:13]
	s_add_i32 m0, s28, 0x16000
	v_lshl_add_u64 v[0:1], s[12:13], 0, v[184:185]
	s_add_u32 s16, s61, s16
	v_lshl_add_u64 v[2:3], v[0:1], 0, s[70:71]
	s_addc_u32 s17, s60, s17
	v_mov_b32_e32 v195, v185
	s_add_i32 s29, s28, 0x2000
	global_load_lds_dwordx4 v[2:3], off
	v_lshl_add_u64 v[10:11], s[16:17], 0, v[194:195]
	s_mov_b32 m0, s28
	s_add_u32 s12, s16, s44
	global_load_lds_dwordx4 v194, s[16:17]
	v_lshl_add_u64 v[8:9], v[10:11], 0, s[70:71]
	s_mov_b32 m0, s29
	s_addc_u32 s13, s17, 0
	s_add_i32 s30, s28, 0x4000
	global_load_lds_dwordx4 v[8:9], off
	v_lshl_add_u64 v[16:17], s[12:13], 0, v[194:195]
	s_mov_b32 m0, s30
	s_add_i32 s31, s28, 0x6000
	global_load_lds_dwordx4 v194, s[12:13]
	v_lshl_add_u64 v[16:17], v[16:17], 0, s[70:71]
	s_mov_b32 m0, s31
	v_writelane_b32 v255, s61, 0
	global_load_lds_dwordx4 v[16:17], off
	s_cmp_eq_u32 s6, 1
	s_mov_b64 vcc, s[66:67]
	s_mov_b64 s[46:47], s[64:65]
	s_mov_b32 s24, s76
	s_mov_b64 s[38:39], s[62:63]
	v_writelane_b32 v255, s60, 1
	s_cselect_b64 s[50:51], -1, 0
	s_cmp_lg_u32 s6, 1
	s_mov_b32 s45, s71
	s_cbranch_scc1 .LBB0_348
	s_mov_b32 s98, 1

.LBB0_404:
	s_andn2_b64 vcc, exec, s[12:13]
	s_mov_b64 s[42:43], 0x2c000
	s_cbranch_vccnz .LBB0_445
	v_mov_b32_e32 v15, v241
	s_and_b64 vcc, exec, s[14:15]
	v_readfirstlane_b32 s0, v15
	s_cbranch_vccnz .LBB0_445
	s_waitcnt lgkmcnt(0)
	v_bfe_i32 v1, v15, 27, 1
	v_lshlrev_b32_e32 v0, 4, v15
	v_lshrrev_b32_e32 v1, 22, v1
	v_add_u32_e32 v1, v0, v1
	v_and_b32_e32 v1, 0xfffffc00, v1
	v_sub_u32_e32 v0, v0, v1
	v_lshrrev_b32_e32 v1, 4, v0
	v_ashrrev_i32_e32 v3, 31, v15
	v_bitop3_b32 v0, v1, v0, 32 bitop3:0x6c
	v_lshrrev_b32_e32 v3, 26, v3
	v_ashrrev_i32_e32 v1, 31, v0
	v_add_u32_e32 v3, v15, v3
	v_lshrrev_b32_e32 v1, 26, v1
	v_ashrrev_i32_e32 v3, 6, v3
	v_add_u32_e32 v1, v0, v1
	v_lshlrev_b32_e32 v4, 3, v3
	v_ashrrev_i32_e32 v2, 6, v1
	v_and_b32_e32 v4, -16, v4
	s_lshl_b32 s6, s23, 9
	v_add_u32_e32 v4, v2, v4
	v_and_b32_e32 v2, 3, v2
	s_mov_b32 s9, 0x7fffffe0
	v_readlane_b32 s10, v254, 37
	v_and_or_b32 v2, v4, s9, v2
	v_and_b32_e32 v1, 0xc0, v1
	s_mul_hi_i32 s9, s6, s10
	s_mul_i32 s13, s6, s10
	v_readlane_b32 s10, v254, 35
	s_ashr_i32 s1, s0, 6
	v_lshrrev_b32_e32 v5, 2, v4
	v_lshlrev_b32_e32 v6, 1, v4
	v_sub_u32_e32 v0, v0, v1
	v_readlane_b32 s11, v254, 36
	s_mov_b32 s14, s10
	s_ashr_i32 s12, s0, 8
	s_lshl_b32 s70, s23, 7
	s_lshl_b32 s8, s23, 8
	s_lshl_b32 s19, s1, 10
	v_and_b32_e32 v5, 4, v5
	v_and_b32_e32 v6, 24, v6
	v_lshlrev_b32_e32 v3, 5, v3
	v_ashrrev_i16_sdwa v0, v238, sext(v0) dst_sel:DWORD dst_unused:UNUSED_PAD src0_sel:DWORD src1_sel:BYTE_0
	s_mul_i32 s11, s6, s14
	v_or3_b32 v2, v2, v5, v6
	v_and_b32_e32 v12, 32, v3
	v_bfe_i32 v13, v0, 0, 16
	s_mul_hi_i32 s10, s6, s10
	s_add_u32 s14, s40, s11
	v_mul_lo_u32 v2, v2, s23
	v_add_u32_e32 v0, v12, v13
	s_addc_u32 s15, s41, s10
	s_add_i32 s20, s19, 0
	v_add_lshl_u32 v184, v2, v0, 1
	s_add_i32 m0, s20, 0x10000
	v_mul_lo_u32 v14, v4, s23
	v_lshl_add_u64 v[4:5], s[14:15], 0, v[184:185]
	global_load_lds_dwordx4 v184, s[14:15]
	s_add_i32 m0, s20, 0x12000
	v_lshl_add_u64 v[6:7], v[4:5], 0, s[70:71]
	s_add_u32 s10, s14, s8
	global_load_lds_dwordx4 v[6:7], off
	s_addc_u32 s11, s15, 0
	s_add_i32 m0, s20, 0x14000
	v_add_lshl_u32 v194, v0, v14, 1
	global_load_lds_dwordx4 v184, s[10:11]
	s_add_i32 m0, s20, 0x16000
	v_lshl_add_u64 v[0:1], s[10:11], 0, v[184:185]
	s_add_u32 s16, s66, s13
	v_lshl_add_u64 v[2:3], v[0:1], 0, s[70:71]
	s_addc_u32 s17, s67, s9
	v_mov_b32_e32 v195, v185
	s_add_i32 s25, s20, 0x2000
	global_load_lds_dwordx4 v[2:3], off
	v_lshl_add_u64 v[10:11], s[16:17], 0, v[194:195]
	s_mov_b32 m0, s20
	s_add_u32 s10, s16, s8
	global_load_lds_dwordx4 v194, s[16:17]
	v_lshl_add_u64 v[8:9], v[10:11], 0, s[70:71]
	s_mov_b32 m0, s25
	s_addc_u32 s11, s17, 0
	s_add_i32 s26, s20, 0x4000
	global_load_lds_dwordx4 v[8:9], off
	v_lshl_add_u64 v[16:17], s[10:11], 0, v[194:195]
	s_mov_b32 m0, s26
	s_add_i32 s27, s20, 0x6000
	global_load_lds_dwordx4 v194, s[10:11]
	v_lshl_add_u64 v[16:17], v[16:17], 0, s[70:71]
	s_mov_b32 m0, s27
	s_cmp_eq_u32 s12, 1
	global_load_lds_dwordx4 v[16:17], off
	v_mov_b64_e32 v[192:193], 0x1ff
	v_mov_b64_e32 v[190:191], 0x200
	s_cselect_b64 s[10:11], -1, 0
	s_cmp_lg_u32 s12, 1
	s_mov_b32 s9, s71
	s_cbranch_scc1 .LBB0_408
	s_mov_b32 s98, 1

.LBB0_451:
	v_ashrrev_i32_e32 v2, 31, v6
	v_lshrrev_b32_e32 v2, 26, v2
	v_add_u32_e32 v2, v6, v2
	v_ashrrev_i32_e32 v7, 6, v2
	v_bfe_i32 v2, v6, 27, 1
	v_lshlrev_b32_e32 v1, 4, v6
	v_lshrrev_b32_e32 v2, 22, v2
	v_add_u32_e32 v2, v1, v2
	v_and_b32_e32 v2, 0xfffffc00, v2
	v_sub_u32_e32 v1, v1, v2
	v_lshrrev_b32_e32 v2, 4, v1
	v_bitop3_b32 v1, v2, v1, 32 bitop3:0x6c
	v_ashrrev_i32_e32 v3, 31, v1
	v_lshrrev_b32_e32 v3, 26, v3
	v_add_u32_e32 v3, v1, v3
	v_lshlrev_b32_e32 v2, 3, v7
	v_ashrrev_i32_e32 v8, 6, v3
	v_and_b32_e32 v3, 0xc0, v3
	v_and_b32_e32 v2, -16, v2
	v_sub_u32_e32 v1, v1, v3
	v_readlane_b32 s8, v254, 20
	v_add_u32_e32 v2, v8, v2
	v_ashrrev_i16_sdwa v1, v238, sext(v1) dst_sel:DWORD dst_unused:UNUSED_PAD src0_sel:DWORD src1_sel:BYTE_0
	v_readlane_b32 s9, v254, 21
	s_add_u32 s14, s22, s8
	v_lshlrev_b32_e32 v4, 5, v7
	v_bfe_i32 v9, v1, 0, 16
	v_lshlrev_b32_e32 v1, 1, v2
	v_lshrrev_b32_e32 v3, 2, v2
	v_and_b32_e32 v5, 3, v8
	s_mov_b32 s6, 0x1fffe0
	s_addc_u32 s15, s23, s9
	s_ashr_i32 s11, s10, 6
	v_and_b32_e32 v4, 32, v4
	v_and_b32_e32 v1, 24, v1
	v_and_b32_e32 v3, 4, v3
	v_and_or_b32 v5, v2, s6, v5
	v_or3_b32 v1, v5, v3, v1
	v_add_lshl_u32 v3, v4, v9, 1
	s_lshl_b32 s6, s11, 10
	v_lshl_add_u32 v184, v1, 11, v3
	s_add_i32 s19, s6, 0
	v_lshl_add_u32 v128, v2, 11, v3
	v_lshl_add_u64 v[2:3], s[14:15], 0, v[184:185]
	s_add_i32 m0, s19, 0x10000
	v_lshl_add_u64 v[4:5], v[2:3], 0, s[34:35]
	global_load_lds_dwordx4 v184, s[14:15]
	s_add_i32 m0, s19, 0x12000
	v_readlane_b32 s8, v254, 22
	global_load_lds_dwordx4 v[4:5], off
	v_lshl_add_u64 v[4:5], v[2:3], 0, s[92:93]
	s_add_i32 m0, s19, 0x14000
	v_mov_b32_e32 v129, v185
	global_load_lds_dwordx4 v[4:5], off
	v_lshl_add_u64 v[4:5], v[2:3], 0, s[52:53]
	s_add_i32 m0, s19, 0x16000
	v_readlane_b32 s9, v254, 23
	global_load_lds_dwordx4 v[4:5], off
	s_mov_b32 m0, s19
	v_lshl_add_u64 v[4:5], s[8:9], 0, v[128:129]
	s_add_i32 s20, s19, 0x2000
	s_nop 0
	global_load_lds_dwordx4 v128, s[8:9]
	v_readlane_b32 s8, v254, 24
	v_lshl_add_u64 v[10:11], v[4:5], 0, s[34:35]
	s_mov_b32 m0, s20
	v_readlane_b32 s9, v254, 25
	s_add_i32 s24, s19, 0x4000
	global_load_lds_dwordx4 v[10:11], off
	v_lshl_add_u64 v[10:11], s[8:9], 0, v[128:129]
	s_mov_b32 m0, s24
	s_add_i32 s25, s19, 0x6000
	global_load_lds_dwordx4 v128, s[8:9]
	v_lshl_add_u64 v[10:11], v[10:11], 0, s[34:35]
	s_mov_b32 m0, s25
	s_ashr_i32 s16, s10, 8
	global_load_lds_dwordx4 v[10:11], off
	s_cmp_eq_u32 s16, 1
	s_cselect_b64 s[8:9], -1, 0
	s_cmp_lg_u32 s16, 1
	s_cbranch_scc1 .LBB0_453
	s_mov_b32 s98, 1

.LBB0_471:
	s_andn2_b64 vcc, exec, s[8:9]
	s_cbranch_vccnz .LBB0_490
	v_readlane_b32 s8, v252, 59
	v_mov_b32_e32 v4, v241
	v_readlane_b32 s9, v252, 60
	s_andn2_b64 vcc, exec, s[8:9]
	v_readfirstlane_b32 s10, v4
	s_cbranch_vccnz .LBB0_490
	s_waitcnt lgkmcnt(0)
	v_bfe_i32 v1, v4, 27, 1
	v_lshlrev_b32_e32 v0, 4, v4
	v_lshrrev_b32_e32 v1, 22, v1
	v_add_u32_e32 v1, v0, v1
	v_and_b32_e32 v1, 0xfffffc00, v1
	v_sub_u32_e32 v0, v0, v1
	v_lshrrev_b32_e32 v1, 4, v0
	v_ashrrev_i32_e32 v2, 31, v4
	v_bitop3_b32 v0, v1, v0, 32 bitop3:0x6c
	v_lshrrev_b32_e32 v2, 26, v2
	v_ashrrev_i32_e32 v1, 31, v0
	v_add_u32_e32 v2, v4, v2
	s_and_b64 s[8:9], s[0:1], exec
	s_mov_b32 s6, 0xa0000
	v_readlane_b32 s12, v252, 39
	v_lshrrev_b32_e32 v1, 26, v1
	v_ashrrev_i32_e32 v6, 6, v2
	s_cselect_b32 s6, s6, 0x60000
	v_readlane_b32 s18, v252, 45
	v_add_u32_e32 v1, v0, v1
	v_lshlrev_b32_e32 v2, 3, v6
	v_readlane_b32 s13, v252, 40
	v_readlane_b32 s19, v252, 46
	s_add_u32 s12, s18, s6
	v_ashrrev_i32_e32 v5, 6, v1
	v_and_b32_e32 v2, -16, v2
	v_readlane_b32 s16, v252, 43
	s_addc_u32 s13, s19, 0
	s_ashr_i32 s11, s10, 6
	v_add_u32_e32 v2, v5, v2
	v_and_b32_e32 v3, 3, v5
	s_mov_b32 s8, 0x1fffe0
	v_readlane_b32 s14, v252, 41
	s_ashr_i32 s16, s10, 8
	s_lshl_b32 s6, s11, 10
	v_and_or_b32 v3, v2, s8, v3
	v_readlane_b32 s8, v254, 20
	v_readlane_b32 s15, v252, 42
	v_readlane_b32 s9, v254, 21
	s_add_u32 s14, s22, s8
	v_lshrrev_b32_e32 v7, 2, v2
	v_lshlrev_b32_e32 v8, 1, v2
	v_and_b32_e32 v1, 0xc0, v1
	s_addc_u32 s15, s23, s9
	v_readlane_b32 s8, v254, 18
	v_and_b32_e32 v7, 4, v7
	v_and_b32_e32 v8, 24, v8
	v_sub_u32_e32 v0, v0, v1
	v_readlane_b32 s9, v254, 19
	v_or3_b32 v3, v3, v7, v8
	v_lshlrev_b32_e32 v7, 5, v6
	v_ashrrev_i16_sdwa v0, v238, sext(v0) dst_sel:DWORD dst_unused:UNUSED_PAD src0_sel:DWORD src1_sel:BYTE_0
	s_lshl_b64 s[8:9], s[8:9], 2
	v_and_b32_e32 v8, 32, v7
	v_bfe_i32 v7, v0, 0, 16
	s_add_u32 s8, s12, s8
	v_add_lshl_u32 v0, v8, v7, 1
	s_addc_u32 s9, s13, s9
	v_lshlrev_b32_sdwa v184, v239, v4 dst_sel:DWORD dst_unused:UNUSED_PAD src0_sel:DWORD src1_sel:BYTE_0
	v_lshl_add_u32 v128, v3, 11, v0
	v_lshl_add_u32 v130, v2, 11, v0
	v_lshl_add_u64 v[0:1], s[8:9], 0, v[184:185]
	v_mov_b32_e32 v129, v185
	s_add_i32 s19, s6, 0
	global_load_dword v134, v[0:1], off
	v_lshl_add_u64 v[0:1], s[14:15], 0, v[128:129]
	s_add_i32 m0, s19, 0x10000
	v_lshl_add_u64 v[2:3], v[0:1], 0, s[34:35]
	global_load_lds_dwordx4 v128, s[14:15]
	s_add_i32 m0, s19, 0x12000
	v_readlane_b32 s8, v254, 22
	global_load_lds_dwordx4 v[2:3], off
	v_lshl_add_u64 v[2:3], v[0:1], 0, s[92:93]
	s_add_i32 m0, s19, 0x14000
	v_mov_b32_e32 v131, v185
	global_load_lds_dwordx4 v[2:3], off
	v_lshl_add_u64 v[2:3], v[0:1], 0, s[52:53]
	s_add_i32 m0, s19, 0x16000
	v_readlane_b32 s9, v254, 23
	global_load_lds_dwordx4 v[2:3], off
	s_mov_b32 m0, s19
	v_lshl_add_u64 v[2:3], s[8:9], 0, v[130:131]
	s_add_i32 s20, s19, 0x2000
	s_nop 0
	global_load_lds_dwordx4 v130, s[8:9]
	v_readlane_b32 s8, v254, 24
	v_lshl_add_u64 v[8:9], v[2:3], 0, s[34:35]
	s_mov_b32 m0, s20
	v_readlane_b32 s9, v254, 25
	s_add_i32 s24, s19, 0x4000
	global_load_lds_dwordx4 v[8:9], off
	v_lshl_add_u64 v[8:9], s[8:9], 0, v[130:131]
	s_mov_b32 m0, s24
	s_add_i32 s25, s19, 0x6000
	global_load_lds_dwordx4 v130, s[8:9]
	v_lshl_add_u64 v[8:9], v[8:9], 0, s[34:35]
	s_mov_b32 m0, s25
	s_cmp_eq_u32 s16, 1
	global_load_lds_dwordx4 v[8:9], off
	s_cselect_b64 s[8:9], -1, 0
	s_cmp_lg_u32 s16, 1
	v_readlane_b32 s17, v252, 44
	s_cbranch_scc1 .LBB0_475
	s_mov_b32 s98, 1

.LBB0_495:
	v_ashrrev_i32_e32 v2, 31, v6
	v_lshrrev_b32_e32 v2, 26, v2
	v_add_u32_e32 v2, v6, v2
	v_ashrrev_i32_e32 v7, 6, v2
	v_bfe_i32 v2, v6, 27, 1
	s_waitcnt lgkmcnt(0)
	v_lshlrev_b32_e32 v1, 4, v6
	v_lshrrev_b32_e32 v2, 22, v2
	v_add_u32_e32 v2, v1, v2
	v_and_b32_e32 v2, 0xfffffc00, v2
	v_sub_u32_e32 v1, v1, v2
	v_lshrrev_b32_e32 v2, 4, v1
	v_bitop3_b32 v1, v2, v1, 32 bitop3:0x6c
	v_ashrrev_i32_e32 v3, 31, v1
	v_lshrrev_b32_e32 v3, 26, v3
	v_add_u32_e32 v3, v1, v3
	v_lshlrev_b32_e32 v2, 3, v7
	v_ashrrev_i32_e32 v8, 6, v3
	v_and_b32_e32 v3, 0xc0, v3
	v_and_b32_e32 v2, -16, v2
	v_sub_u32_e32 v1, v1, v3
	v_readlane_b32 s0, v254, 28
	v_add_u32_e32 v2, v8, v2
	v_ashrrev_i16_sdwa v1, v238, sext(v1) dst_sel:DWORD dst_unused:UNUSED_PAD src0_sel:DWORD src1_sel:BYTE_0
	v_readlane_b32 s1, v254, 29
	s_add_u32 s14, s22, s0
	v_lshlrev_b32_e32 v4, 5, v7
	v_bfe_i32 v9, v1, 0, 16
	v_lshlrev_b32_e32 v1, 1, v2
	v_lshrrev_b32_e32 v3, 2, v2
	v_and_b32_e32 v5, 3, v8
	s_mov_b32 s0, 0x3fffe0
	s_addc_u32 s15, s23, s1
	s_ashr_i32 s9, s8, 6
	v_and_b32_e32 v4, 32, v4
	v_and_b32_e32 v1, 24, v1
	v_and_b32_e32 v3, 4, v3
	v_and_or_b32 v5, v2, s0, v5
	v_or3_b32 v1, v5, v3, v1
	v_add_lshl_u32 v3, v4, v9, 1
	s_lshl_b32 s6, s9, 10
	v_lshl_add_u32 v184, v1, 10, v3
	s_add_i32 s19, s6, 0
	v_lshl_add_u32 v160, v2, 10, v3
	v_lshl_add_u64 v[2:3], s[14:15], 0, v[184:185]
	s_add_i32 m0, s19, 0x10000
	v_lshl_add_u64 v[4:5], v[2:3], 0, s[94:95]
	global_load_lds_dwordx4 v184, s[14:15]
	s_add_i32 m0, s19, 0x12000
	v_readlane_b32 s0, v254, 30
	global_load_lds_dwordx4 v[4:5], off
	v_lshl_add_u64 v[4:5], v[2:3], 0, s[34:35]
	s_add_i32 m0, s19, 0x14000
	v_mov_b32_e32 v161, v185
	global_load_lds_dwordx4 v[4:5], off
	v_lshl_add_u64 v[4:5], v[2:3], 0, s[90:91]
	s_add_i32 m0, s19, 0x16000
	v_readlane_b32 s1, v254, 31
	global_load_lds_dwordx4 v[4:5], off
	s_mov_b32 m0, s19
	v_lshl_add_u64 v[4:5], s[0:1], 0, v[160:161]
	s_add_i32 s20, s19, 0x2000
	s_nop 0
	global_load_lds_dwordx4 v160, s[0:1]
	v_readlane_b32 s0, v254, 32
	v_lshl_add_u64 v[10:11], v[4:5], 0, s[94:95]
	s_mov_b32 m0, s20
	v_readlane_b32 s1, v254, 33
	s_add_i32 s24, s19, 0x4000
	global_load_lds_dwordx4 v[10:11], off
	v_lshl_add_u64 v[10:11], s[0:1], 0, v[160:161]
	s_mov_b32 m0, s24
	s_add_i32 s25, s19, 0x6000
	global_load_lds_dwordx4 v160, s[0:1]
	v_lshl_add_u64 v[10:11], v[10:11], 0, s[94:95]
	s_mov_b32 m0, s25
	s_ashr_i32 s12, s8, 8
	global_load_lds_dwordx4 v[10:11], off
	s_cmp_eq_u32 s12, 1
	s_cselect_b64 s[0:1], -1, 0
	s_cmp_lg_u32 s12, 1
	s_movk_i32 s18, 0xb00
	s_cbranch_scc1 .LBB0_497
	s_mov_b32 s98, 1
